# combined retention-side latency cuts: ret_unit_c gn-weight preload plus sample-loop store-drain overlap, on the v104 tile placement
# speedup vs baseline: 1.0071x; 1.0045x over previous
; #define LAS __attribute__((address_space(3)))
; template <bool WITH_K>
; __device__ __forceinline__ void ret_load_qk(PR P, LAS bf16_t* QP, LAS bf16_t* KB, unsigned (&kth)[4][4], const int tidv, const int row0, const int n, const int h, const float kd0, const float g32) {
;     const bf16_t* PS = (const bf16_t*)(P.ws + WS_BIG); const float* rc = (const float*)(P.ws + WS_ROPE); const float* rs = rc + 2052 * 64;
;     float kd = kd0;
; #pragma unroll
;     for (int it = 0; it < 4; ++it) { const int idx = it * 512 + tidv, i = idx >> 4, f = (idx & 15) * 4;
;         const bf16_t* src = PS + (size_t)(row0 + i) * NCOLS + 1792 + h * 128;
;         const u32x2 q1 = *(const u32x2*)(src + f), q2 = *(const u32x2*)(src + 64 + f);
;         u32x2 k1 = (u32x2){0u, 0u}, k2 = k1; if (WITH_K) { k1 = *(const u32x2*)(src + 512 + f); k2 = *(const u32x2*)(src + 576 + f); }
;         const float4 cs = *(const float4*)(rc + (size_t)(n * 128 + i) * 64 + f), sn = *(const float4*)(rs + (size_t)(n * 128 + i) * 64 + f);
;         const float c4[4] = {cs.x, cs.y, cs.z, cs.w}, s4[4] = {sn.x, sn.y, sn.z, sn.w};
;         const float qa[4] = {lo_bf(q1.x), hi_bf(q1.x), lo_bf(q1.y), hi_bf(q1.y)}, qb[4] = {lo_bf(q2.x), hi_bf(q2.x), lo_bf(q2.y), hi_bf(q2.y)};
;         float qo1[4], qo2[4];
; #pragma unroll
;         for (int x = 0; x < 4; ++x) { qo1[x] = qa[x] * c4[x] - qb[x] * s4[x]; qo2[x] = qa[x] * s4[x] + qb[x] * c4[x]; }
;         u32x2 w; w.x = pg8::cvt_pk_bf16(qo1[0], qo1[1]); w.y = pg8::cvt_pk_bf16(qo1[2], qo1[3]); *(LAS u32x2*)(QP + i * RS + f) = w;
;         w.x = pg8::cvt_pk_bf16(qo2[0], qo2[1]); w.y = pg8::cvt_pk_bf16(qo2[2], qo2[3]); *(LAS u32x2*)(QP + i * RS + 64 + f) = w;
; __device__ __forceinline__ void ret_unit_c(PR P, LAS unsigned char* lds, const int bh, const int n, const int wv) {
;     ...
;     const int tid = fresh_tid(wv), lane = tid & 63, wid = tid >> 6, wr = wid >> 1, wc = wid & 1, fr = lane & 15, fq = lane >> 4;
;     const int b = bh >> 2, h = bh & 3;
;     const bf16_t* PS = (const bf16_t*)(P.ws + WS_BIG); bf16_t* Y = (bf16_t*)(P.ws + WS_XN); const bf16_t* KVB = kvb_ptr(P.ws, bh) + (size_t)n * 16384;
;     const float lg2 = log2f(1.0f - exp2f(-5.0f - (float)h));
;     const int row0 = b * 2048 + n * 128;
;     unsigned kth[4][4];
;     ret_load_qk<false>(P, QP, QP, kth, tid, row0, n, h, 0.f, 0.f);
; #pragma unroll
.LBB0_654:
	s_add_i32 s18, s2, s28
	s_ashr_i32 s18, s18, 4
	s_and_b32 s44, s18, 3
	s_sub_i32 s26, s18, 29
	s_ashr_i32 s27, s18, 31
	s_cmp_lt_i32 s18, 29
	s_cselect_b32 s45, s29, 0x1444800
	s_cselect_b32 s27, s27, 0
	s_cselect_b32 s26, s18, s26
	s_add_u32 s45, s10, s45
	s_addc_u32 s46, s11, 0
	s_lshl_b64 s[26:27], s[26:27], 19
	s_add_u32 s26, s45, s26
	s_addc_u32 s27, s46, s27
	v_cvt_f32_ubyte0_e32 v0, s44
	s_add_u32 s26, s26, s7
	v_sub_f32_e32 v34, 0xc0a00000, v0
	s_addc_u32 s27, s27, 0
	v_cmp_gt_f32_e32 vcc, s30, v34
	s_and_b64 s[46:47], vcc, exec
	s_cselect_b32 s55, 0xffffffc0, 0
	s_lshl_b32 s18, s18, 9
	v_mbcnt_lo_u32_b32 v2, -1, 0
	v_mbcnt_hi_u32_b32 v2, -1, v2
	s_and_b32 s18, s18, 0xfffff800
	v_add_u32_e32 v3, s33, v2
	s_or_b32 s45, s18, s6
	v_lshlrev_b32_e32 v0, 2, v2
	v_ashrrev_i32_e32 v46, 4, v3
	v_and_b32_e32 v6, 60, v0
	v_add_u32_e32 v4, s45, v46
	v_lshlrev_b32_e32 v28, 2, v6
	v_mad_i64_i32 v[4:5], s[46:47], v4, s31, v[30:31]
	s_lshl_b32 s18, s44, 8
	v_lshl_add_u64 v[0:1], s[14:15], 0, v[28:29]
	v_lshl_add_u64 v[20:21], s[16:17], 0, v[28:29]
	v_lshl_add_u64 v[4:5], v[4:5], 0, s[18:19]
	v_lshlrev_b32_e32 v28, 1, v6
	v_lshl_add_u64 v[4:5], v[4:5], 0, v[28:29]
	v_cndmask_b32_e32 v35, 0, v62, vcc
	v_lshl_add_u64 v[6:7], v[4:5], 0, s[20:21]
	v_add_co_u32_e32 v4, vcc, s34, v4
	v_add_f32_e32 v34, v34, v35
	s_nop 0
	v_addc_co_u32_e32 v5, vcc, 0, v5, vcc
	global_load_dwordx2 v[22:23], v[4:5], off offset:1536
	global_load_dwordx2 v[24:25], v[6:7], off offset:128
	v_add_u32_e32 v4, s6, v46
	v_ashrrev_i32_e32 v5, 31, v4
	v_lshlrev_b64 v[8:9], 8, v[4:5]
	v_add_u32_e32 v4, 0x200, v3
	v_ashrrev_i32_e32 v47, 4, v4
	v_add_u32_e32 v4, s45, v47
	v_mad_i64_i32 v[4:5], s[46:47], v4, s31, v[30:31]
	v_lshl_add_u64 v[4:5], v[4:5], 0, s[18:19]
	v_lshl_add_u64 v[12:13], v[4:5], 0, v[28:29]
	v_add_co_u32_e32 v4, vcc, s34, v12
	v_exp_f32_e32 v34, v34
	s_nop 0
	v_addc_co_u32_e32 v5, vcc, 0, v13, vcc
	v_lshl_add_u64 v[12:13], v[12:13], 0, s[20:21]
	global_load_dwordx2 v[26:27], v[4:5], off offset:1536
	global_load_dwordx2 v[32:33], v[12:13], off offset:128
	v_lshl_add_u64 v[4:5], v[20:21], 0, v[8:9]
	global_load_dwordx4 v[4:7], v[4:5], off
	v_lshl_add_u64 v[8:9], v[0:1], 0, v[8:9]
	v_add_u32_e32 v12, s6, v47
	global_load_dwordx4 v[8:11], v[8:9], off
	v_ashrrev_i32_e32 v13, 31, v12
	v_lshlrev_b64 v[12:13], 8, v[12:13]
	v_lshl_add_u64 v[16:17], v[0:1], 0, v[12:13]
	v_lshl_add_u64 v[12:13], v[20:21], 0, v[12:13]
	global_load_dwordx4 v[12:15], v[12:13], off
	s_nop 0
	global_load_dwordx4 v[16:19], v[16:17], off
	v_ldexp_f32 v34, v34, s55
	v_sub_f32_e32 v57, 1.0, v34
	v_mul_lo_u32 v48, v46, s35
	v_add3_u32 v44, 0, v48, v28
	v_mul_lo_u32 v49, v47, s35
	v_bfe_u32 v56, v3, 6, 1
	s_waitcnt vmcnt(7)
	v_lshlrev_b32_e32 v34, 16, v22
	v_and_b32_e32 v35, 0xffff0000, v22
	s_waitcnt vmcnt(6)
	v_lshlrev_b32_e32 v36, 16, v24
	v_and_b32_e32 v37, 0xffff0000, v24
	v_lshlrev_b32_e32 v22, 16, v23
	v_and_b32_e32 v23, 0xffff0000, v23
	v_lshlrev_b32_e32 v24, 16, v25
	v_and_b32_e32 v25, 0xffff0000, v25
	s_waitcnt vmcnt(5)
	v_lshlrev_b32_e32 v38, 16, v26
	v_and_b32_e32 v39, 0xffff0000, v26
	s_waitcnt vmcnt(3)
	v_pk_mul_f32 v[40:41], v[4:5], v[34:35]
	v_pk_mul_f32 v[4:5], v[4:5], v[36:37]
	v_pk_mul_f32 v[42:43], v[6:7], v[22:23]
	v_pk_mul_f32 v[6:7], v[6:7], v[24:25]
	s_waitcnt vmcnt(2)
	v_pk_fma_f32 v[36:37], v[8:9], v[36:37], v[40:41]
	v_pk_fma_f32 v[4:5], v[8:9], v[34:35], v[4:5] neg_lo:[0,0,1] neg_hi:[0,0,1]
	v_pk_fma_f32 v[8:9], v[10:11], v[24:25], v[42:43]
	v_pk_fma_f32 v[6:7], v[10:11], v[22:23], v[6:7] neg_lo:[0,0,1] neg_hi:[0,0,1]
	v_cvt_pk_bf16_f32 v4, v4, v5
	v_cvt_pk_bf16_f32 v5, v6, v7
	v_cvt_pk_bf16_f32 v6, v36, v37
	v_cvt_pk_bf16_f32 v7, v8, v9
	ds_write2_b64 v44, v[4:5], v[6:7] offset1:16
	v_lshlrev_b32_e32 v4, 16, v32
	v_and_b32_e32 v5, 0xffff0000, v32
	s_waitcnt vmcnt(1)
	v_pk_mul_f32 v[6:7], v[12:13], v[38:39]
	v_lshlrev_b32_e32 v8, 16, v27
	v_and_b32_e32 v9, 0xffff0000, v27
	s_waitcnt vmcnt(0)
	v_pk_fma_f32 v[6:7], v[16:17], v[4:5], v[6:7]
	v_pk_mul_f32 v[4:5], v[12:13], v[4:5]
	v_lshlrev_b32_e32 v10, 16, v33
	v_and_b32_e32 v11, 0xffff0000, v33
	v_pk_mul_f32 v[12:13], v[14:15], v[8:9]
	v_pk_fma_f32 v[4:5], v[16:17], v[38:39], v[4:5] neg_lo:[0,0,1] neg_hi:[0,0,1]
	v_pk_fma_f32 v[12:13], v[18:19], v[10:11], v[12:13]
	v_pk_mul_f32 v[10:11], v[14:15], v[10:11]
	v_cvt_pk_bf16_f32 v4, v4, v5
	v_pk_fma_f32 v[8:9], v[18:19], v[8:9], v[10:11] neg_lo:[0,0,1] neg_hi:[0,0,1]
	v_cvt_pk_bf16_f32 v6, v6, v7
	v_cvt_pk_bf16_f32 v5, v8, v9
	v_add3_u32 v8, 0, v49, v28
	v_cvt_pk_bf16_f32 v7, v12, v13
	ds_write2_b64 v8, v[4:5], v[6:7] offset1:16
	v_add_u32_e32 v4, 0x400, v3
	v_ashrrev_i32_e32 v50, 4, v4
	v_add_u32_e32 v4, s45, v50
	v_mad_i64_i32 v[4:5], s[46:47], v4, s31, v[30:31]
	v_lshl_add_u64 v[4:5], v[4:5], 0, s[18:19]
	v_lshl_add_u64 v[4:5], v[4:5], 0, v[28:29]
	v_lshl_add_u64 v[6:7], v[4:5], 0, s[20:21]
	v_add_co_u32_e32 v4, vcc, s34, v4
	v_mul_lo_u32 v52, v50, s35
	s_nop 0
	v_addc_co_u32_e32 v5, vcc, 0, v5, vcc
	global_load_dwordx2 v[22:23], v[4:5], off offset:1536
	global_load_dwordx2 v[24:25], v[6:7], off offset:128
	v_add_u32_e32 v4, 0x600, v3
	v_ashrrev_i32_e32 v51, 4, v4
	v_add_u32_e32 v4, s45, v51
	v_mad_i64_i32 v[4:5], s[46:47], v4, s31, v[30:31]
	v_lshl_add_u64 v[4:5], v[4:5], 0, s[18:19]
	v_lshl_add_u64 v[4:5], v[4:5], 0, v[28:29]
	v_add_co_u32_e32 v6, vcc, s34, v4
	v_add_u32_e32 v8, s6, v51
	s_nop 0
	v_addc_co_u32_e32 v7, vcc, 0, v5, vcc
	v_lshl_add_u64 v[4:5], v[4:5], 0, s[20:21]
	global_load_dwordx2 v[26:27], v[6:7], off offset:1536
	global_load_dwordx2 v[32:33], v[4:5], off offset:128
	v_add_u32_e32 v4, s6, v50
	v_ashrrev_i32_e32 v5, 31, v4
	v_lshlrev_b64 v[12:13], 8, v[4:5]
	v_ashrrev_i32_e32 v9, 31, v8
	v_lshl_add_u64 v[4:5], v[20:21], 0, v[12:13]
	v_lshlrev_b64 v[16:17], 8, v[8:9]
	global_load_dwordx4 v[4:7], v[4:5], off
	v_lshl_add_u64 v[8:9], v[20:21], 0, v[16:17]
	v_lshl_add_u64 v[12:13], v[0:1], 0, v[12:13]
	global_load_dwordx4 v[8:11], v[8:9], off
	v_lshl_add_u64 v[0:1], v[0:1], 0, v[16:17]
	global_load_dwordx4 v[12:15], v[12:13], off
	v_mul_lo_u32 v53, v51, s35
	global_load_dwordx4 v[16:19], v[0:1], off
	v_lshlrev_b32_e32 v216, 4, v2
	v_and_b32_e32 v216, 0xf0, v216
	v_mov_b32_e32 v217, 0
	v_lshl_add_u64 v[218:219], s[26:27], 0, v[216:217]
	v_lshlrev_b32_e32 v220, 7, v46
	v_ashrrev_i32_e32 v221, 31, v220
	v_lshl_add_u64 v[220:221], v[220:221], 1, v[218:219]
	v_lshlrev_b32_e32 v222, 7, v47
	v_ashrrev_i32_e32 v223, 31, v222
	v_lshl_add_u64 v[222:223], v[222:223], 1, v[218:219]
	v_lshlrev_b32_e32 v224, 7, v50
	v_ashrrev_i32_e32 v225, 31, v224
	v_lshl_add_u64 v[224:225], v[224:225], 1, v[218:219]
	v_lshlrev_b32_e32 v226, 7, v51
	v_ashrrev_i32_e32 v227, 31, v226
	v_lshl_add_u64 v[226:227], v[226:227], 1, v[218:219]
	global_load_dwordx4 v[200:203], v[220:221], off
	global_load_dwordx4 v[204:207], v[222:223], off
	global_load_dwordx4 v[208:211], v[224:225], off
	global_load_dwordx4 v[212:215], v[226:227], off
	v_add3_u32 v54, 0, v52, v28
	v_add3_u32 v28, 0, v53, v28
	s_waitcnt vmcnt(11)
; #define LAS __attribute__((address_space(3)))
; __device__ __forceinline__ void ret_unit_c(PR P, LAS unsigned char* lds, const int bh, const int n, const int wv) {
;     ...
;     for (int it = 0; it < 4; ++it) { const int idx = it * 512 + tid, e = idx >> 4, d8 = (idx & 15) * 8;
;         *(LAS u32x4*)(ST + e * RS + d8) = *(const u32x4*)(KVB + e * 128 + d8); }
;     __syncthreads();
;     f32x4 accY[2][4];
; #pragma unroll
;     for (int mt = 0; mt < 2; ++mt)
; #pragma unroll
;         for (int nt = 0; nt < 4; ++nt) accY[mt][nt] = (f32x4){0.f, 0.f, 0.f, 0.f};
; #pragma unroll
;     for (int ks = 0; ks < 4; ++ks) { bf16x8 aq[2];
; #pragma unroll
;         for (int mt = 0; mt < 2; ++mt) aq[mt] = *(const LAS bf16x8*)(QP + (wr * 32 + mt * 16 + fr) * RS + ks * 32 + fq * 8);
; #pragma unroll
;         for (int nt = 0; nt < 4; ++nt) { const bf16x8 bs = *(const LAS bf16x8*)(ST + (wc * 64 + nt * 16 + fr) * RS + ks * 32 + fq * 8);
; #pragma unroll
;             for (int mt = 0; mt < 2; ++mt) accY[mt][nt] = __builtin_amdgcn_mfma_f32_16x16x32_bf16(aq[mt], bs, accY[mt][nt], 0, 0, 0); }
;         __builtin_amdgcn_sched_barrier(0); }
	v_lshlrev_b32_e32 v0, 16, v22
	v_and_b32_e32 v1, 0xffff0000, v22
	s_waitcnt vmcnt(10)
	v_lshlrev_b32_e32 v20, 16, v24
	v_and_b32_e32 v21, 0xffff0000, v24
	v_lshlrev_b32_e32 v22, 16, v23
	v_and_b32_e32 v23, 0xffff0000, v23
	v_lshlrev_b32_e32 v24, 16, v25
	v_and_b32_e32 v25, 0xffff0000, v25
	s_waitcnt vmcnt(9)
	v_lshlrev_b32_e32 v34, 16, v26
	v_and_b32_e32 v35, 0xffff0000, v26
	s_waitcnt vmcnt(8)
	v_lshlrev_b32_e32 v36, 16, v32
	v_and_b32_e32 v37, 0xffff0000, v32
	v_lshlrev_b32_e32 v26, 16, v27
	v_and_b32_e32 v27, 0xffff0000, v27
	v_lshlrev_b32_e32 v32, 16, v33
	v_and_b32_e32 v33, 0xffff0000, v33
	s_waitcnt vmcnt(7)
	v_pk_mul_f32 v[38:39], v[4:5], v[0:1]
	v_pk_mul_f32 v[4:5], v[4:5], v[20:21]
	v_pk_mul_f32 v[40:41], v[6:7], v[22:23]
	v_pk_mul_f32 v[6:7], v[6:7], v[24:25]
	s_waitcnt vmcnt(6)
	v_pk_mul_f32 v[42:43], v[8:9], v[34:35]
	v_pk_mul_f32 v[8:9], v[8:9], v[36:37]
	v_pk_mul_f32 v[44:45], v[10:11], v[26:27]
	v_pk_mul_f32 v[10:11], v[10:11], v[32:33]
	s_waitcnt vmcnt(5)
	v_pk_fma_f32 v[20:21], v[12:13], v[20:21], v[38:39]
	v_pk_fma_f32 v[0:1], v[12:13], v[0:1], v[4:5] neg_lo:[0,0,1] neg_hi:[0,0,1]
	v_pk_fma_f32 v[4:5], v[14:15], v[24:25], v[40:41]
	v_pk_fma_f32 v[6:7], v[14:15], v[22:23], v[6:7] neg_lo:[0,0,1] neg_hi:[0,0,1]
	s_waitcnt vmcnt(4)
	v_pk_fma_f32 v[12:13], v[16:17], v[36:37], v[42:43]
	v_pk_fma_f32 v[8:9], v[16:17], v[34:35], v[8:9] neg_lo:[0,0,1] neg_hi:[0,0,1]
	v_pk_fma_f32 v[14:15], v[18:19], v[32:33], v[44:45]
	v_pk_fma_f32 v[10:11], v[18:19], v[26:27], v[10:11] neg_lo:[0,0,1] neg_hi:[0,0,1]
	v_cvt_pk_bf16_f32 v0, v0, v1
	v_cvt_pk_bf16_f32 v1, v6, v7
	v_cvt_pk_bf16_f32 v6, v20, v21
	v_cvt_pk_bf16_f32 v7, v4, v5
	v_cvt_pk_bf16_f32 v4, v8, v9
	v_cvt_pk_bf16_f32 v5, v10, v11
	v_cvt_pk_bf16_f32 v8, v12, v13
	v_cvt_pk_bf16_f32 v9, v14, v15
	ds_write2_b64 v54, v[0:1], v[6:7] offset1:16
	ds_write2_b64 v28, v[4:5], v[8:9] offset1:16
	v_lshlrev_b32_e32 v0, 4, v2
	v_and_b32_e32 v28, 0xf0, v0
	v_ashrrev_i32_e32 v66, 2, v3
	v_and_b32_e32 v1, 15, v2
	v_and_b32_e32 v3, 0xffffffe0, v66
	v_bfe_u32 v0, v2, 4, 2
	v_or_b32_e32 v23, v3, v1
	v_lshlrev_b32_e32 v20, 4, v0
	v_add_u32_e32 v22, s36, v28
	v_mul_lo_u32 v23, v23, s35
	v_add_u32_e32 v24, v22, v48
	v_add3_u32 v28, 0, v20, v23
	v_add_u32_e32 v25, v22, v49
	v_add_u32_e32 v26, v22, v52
	v_add_u32_e32 v22, v22, v53
	v_lshl_or_b32 v21, v56, 6, v1
	s_waitcnt vmcnt(3)
	ds_write_b128 v24, v[200:203]
	s_waitcnt vmcnt(2)
	ds_write_b128 v25, v[204:207]
	s_waitcnt vmcnt(1)
	ds_write_b128 v26, v[208:211]
	s_waitcnt vmcnt(0)
	ds_write_b128 v22, v[212:215]
	s_waitcnt lgkmcnt(0)
	s_barrier
	ds_read_b128 v[4:7], v28
	v_mul_u32_u24_e32 v8, 0x110, v21
	v_add3_u32 v58, s36, v20, v8
	ds_read_b128 v[8:11], v28 offset:4352
	ds_read_b128 v[12:15], v58
	ds_read_b128 v[16:19], v58 offset:4352
	ds_read_b128 v[32:35], v58 offset:8704
	ds_read_b128 v[36:39], v58 offset:13056
	s_waitcnt lgkmcnt(3)
	v_mfma_f32_16x16x32_bf16 v[20:23], v[4:7], v[12:15], 0
	v_mfma_f32_16x16x32_bf16 v[12:15], v[8:11], v[12:15], 0
	s_waitcnt lgkmcnt(2)
	v_mfma_f32_16x16x32_bf16 v[24:27], v[4:7], v[16:19], 0
	v_mfma_f32_16x16x32_bf16 v[16:19], v[8:11], v[16:19], 0
	s_waitcnt lgkmcnt(1)
	v_mfma_f32_16x16x32_bf16 v[40:43], v[4:7], v[32:35], 0
	v_mfma_f32_16x16x32_bf16 v[32:35], v[8:11], v[32:35], 0
	s_waitcnt lgkmcnt(0)
	v_mfma_f32_16x16x32_bf16 v[4:7], v[4:7], v[36:39], 0
	v_mfma_f32_16x16x32_bf16 v[8:11], v[8:11], v[36:39], 0
	ds_read_b128 v[36:39], v28 offset:64
	ds_read_b128 v[44:47], v28 offset:4416
	ds_read_b128 v[48:51], v58 offset:64
	ds_read_b128 v[52:55], v58 offset:4416
	s_waitcnt lgkmcnt(1)
	v_mfma_f32_16x16x32_bf16 v[20:23], v[36:39], v[48:51], v[20:23]
	v_mfma_f32_16x16x32_bf16 v[12:15], v[44:47], v[48:51], v[12:15]
	s_waitcnt lgkmcnt(0)
	v_mfma_f32_16x16x32_bf16 v[24:27], v[36:39], v[52:55], v[24:27]
	v_mfma_f32_16x16x32_bf16 v[16:19], v[44:47], v[52:55], v[16:19]
	ds_read_b128 v[48:51], v58 offset:8768
	ds_read_b128 v[52:55], v58 offset:13120
	s_waitcnt lgkmcnt(1)
	v_mfma_f32_16x16x32_bf16 v[40:43], v[36:39], v[48:51], v[40:43]
	v_mfma_f32_16x16x32_bf16 v[32:35], v[44:47], v[48:51], v[32:35]
	s_waitcnt lgkmcnt(0)
	v_mfma_f32_16x16x32_bf16 v[4:7], v[36:39], v[52:55], v[4:7]
	v_mfma_f32_16x16x32_bf16 v[8:11], v[44:47], v[52:55], v[8:11]
	ds_read_b128 v[36:39], v28 offset:128
	ds_read_b128 v[44:47], v28 offset:4480
	ds_read_b128 v[48:51], v58 offset:128
	ds_read_b128 v[52:55], v58 offset:4480
	s_waitcnt lgkmcnt(1)
	v_mfma_f32_16x16x32_bf16 v[20:23], v[36:39], v[48:51], v[20:23]
	v_mfma_f32_16x16x32_bf16 v[12:15], v[44:47], v[48:51], v[12:15]
	s_waitcnt lgkmcnt(0)
	v_mfma_f32_16x16x32_bf16 v[24:27], v[36:39], v[52:55], v[24:27]
	v_mfma_f32_16x16x32_bf16 v[16:19], v[44:47], v[52:55], v[16:19]
	ds_read_b128 v[48:51], v58 offset:8832
	ds_read_b128 v[52:55], v58 offset:13184
	s_waitcnt lgkmcnt(1)
	v_mfma_f32_16x16x32_bf16 v[40:43], v[36:39], v[48:51], v[40:43]
	v_mfma_f32_16x16x32_bf16 v[32:35], v[44:47], v[48:51], v[32:35]
	s_waitcnt lgkmcnt(0)
	v_mfma_f32_16x16x32_bf16 v[4:7], v[36:39], v[52:55], v[4:7]
	v_mfma_f32_16x16x32_bf16 v[8:11], v[44:47], v[52:55], v[8:11]
	ds_read_b128 v[36:39], v28 offset:192
	ds_read_b128 v[44:47], v28 offset:4544
	ds_read_b128 v[48:51], v58 offset:192
	ds_read_b128 v[52:55], v58 offset:4544
	s_waitcnt lgkmcnt(1)
	v_mfma_f32_16x16x32_bf16 v[20:23], v[36:39], v[48:51], v[20:23]
	v_mfma_f32_16x16x32_bf16 v[12:15], v[44:47], v[48:51], v[12:15]
	s_waitcnt lgkmcnt(0)
	v_mfma_f32_16x16x32_bf16 v[24:27], v[36:39], v[52:55], v[24:27]
	v_mfma_f32_16x16x32_bf16 v[16:19], v[44:47], v[52:55], v[16:19]
	ds_read_b128 v[48:51], v58 offset:8896
	ds_read_b128 v[52:55], v58 offset:13248
	s_waitcnt lgkmcnt(1)
; __device__ __forceinline__ void ret_unit_c(PR P, LAS unsigned char* lds, const int bh, const int n, const int wv) {
;     ...
; #pragma unroll
;     for (int mt = 0; mt < 2; ++mt)
; #pragma unroll
;         for (int j = 0; j < 4; ++j) { const int r = wr * 32 + mt * 16 + fq * 4 + j; const float qd = exp2f(lg2 * (float)(r + 1));
; #pragma unroll
;             for (int nt = 0; nt < 4; ++nt) YST[r * 132 + wc * 64 + nt * 16 + fr] = accY[mt][nt][j] * qd; }
;     __syncthreads();
;     { const int i = tid >> 2, part = tid & 3; float yv[32]; float s = 0.f;
;       bf16_t* yo = Y + (size_t)(row0 + i) * 1024 + 512 + h * 128 + part * 32;
	v_mfma_f32_16x16x32_bf16 v[40:43], v[36:39], v[48:51], v[40:43]
	v_mfma_f32_16x16x32_bf16 v[32:35], v[44:47], v[48:51], v[32:35]
	s_waitcnt lgkmcnt(0)
	v_mfma_f32_16x16x32_bf16 v[4:7], v[36:39], v[52:55], v[4:7]
	v_mfma_f32_16x16x32_bf16 v[8:11], v[44:47], v[52:55], v[8:11]
	v_cmp_gt_f32_e32 vcc, s37, v57
	s_and_b64 s[26:27], vcc, exec
	s_cselect_b32 s26, 32, 0
	v_ldexp_f32 v36, v57, s26
	v_lshl_or_b32 v0, v0, 2, v3
	v_log_f32_e32 v36, v36
	v_or_b32_e32 v3, 1, v0
	v_cvt_f32_i32_e32 v3, v3
	v_cndmask_b32_e32 v28, 0, v63, vcc
	v_sub_f32_e32 v28, v36, v28
	v_lshlrev_b32_e32 v1, 2, v1
	v_mul_f32_e32 v36, v28, v3
	v_cmp_gt_f32_e32 vcc, s30, v36
	v_lshlrev_b32_e32 v2, 5, v2
	s_nop 0
	v_cndmask_b32_e32 v36, 0, v62, vcc
	v_fmac_f32_e32 v36, v28, v3
	v_exp_f32_e32 v3, v36
	v_cndmask_b32_e32 v37, 0, v64, vcc
	v_lshl_add_u32 v36, v56, 8, 0
	v_ldexp_f32 v3, v3, v37
	v_mul_lo_u32 v37, v0, s40
	v_add3_u32 v1, v36, v1, v37
	v_or_b32_e32 v36, 2, v0
	v_cvt_f32_i32_e32 v36, v36
	v_mul_f32_e32 v20, v3, v20
	v_mul_f32_e32 v24, v3, v24
	v_add_u32_e32 v37, 0x8800, v1
	ds_write2_b32 v37, v20, v24 offset1:16
	v_mul_f32_e32 v24, v28, v36
	v_cmp_gt_f32_e32 vcc, s30, v24
	v_mul_f32_e32 v20, v3, v40
	v_mul_f32_e32 v3, v3, v4
	v_cndmask_b32_e32 v24, 0, v62, vcc
	v_fmac_f32_e32 v24, v28, v36
	v_exp_f32_e32 v24, v24
	ds_write2_b32 v37, v20, v3 offset0:32 offset1:48
	v_or_b32_e32 v20, 3, v0
	v_cvt_f32_i32_e32 v20, v20
	v_cndmask_b32_e32 v3, 0, v64, vcc
	v_ldexp_f32 v3, v24, v3
	v_mul_f32_e32 v4, v3, v21
	v_mul_f32_e32 v21, v3, v25
	ds_write2_b32 v37, v4, v21 offset0:132 offset1:148
	v_mul_f32_e32 v21, v28, v20
	v_cmp_gt_f32_e32 vcc, s30, v21
	v_mul_f32_e32 v4, v3, v41
	v_mul_f32_e32 v3, v3, v5
	v_cndmask_b32_e32 v21, 0, v62, vcc
	v_fmac_f32_e32 v21, v28, v20
	v_exp_f32_e32 v20, v21
	ds_write2_b32 v37, v4, v3 offset0:164 offset1:180
	v_cndmask_b32_e32 v3, 0, v64, vcc
	v_add_u32_e32 v21, 0x8c00, v1
	v_ldexp_f32 v3, v20, v3
	v_add_u32_e32 v20, 4, v0
	v_cvt_f32_i32_e32 v20, v20
	v_mul_f32_e32 v4, v3, v22
	v_mul_f32_e32 v5, v3, v26
	ds_write2_b32 v21, v4, v5 offset0:8 offset1:24
	v_mul_f32_e32 v5, v28, v20
	v_cmp_gt_f32_e32 vcc, s30, v5
	v_mul_f32_e32 v4, v3, v42
	v_mul_f32_e32 v3, v3, v6
	v_cndmask_b32_e32 v5, 0, v62, vcc
	v_fmac_f32_e32 v5, v28, v20
	v_exp_f32_e32 v5, v5
	ds_write2_b32 v21, v4, v3 offset0:40 offset1:56
	v_cndmask_b32_e32 v3, 0, v64, vcc
	v_ldexp_f32 v3, v5, v3
	v_or_b32_e32 v5, 17, v0
	v_cvt_f32_i32_e32 v5, v5
	v_mul_f32_e32 v4, v3, v23
	v_mul_f32_e32 v6, v3, v27
	ds_write2_b32 v21, v4, v6 offset0:140 offset1:156
	v_mul_f32_e32 v6, v28, v5
	v_cmp_gt_f32_e32 vcc, s30, v6
	v_mul_f32_e32 v4, v3, v43
	v_mul_f32_e32 v3, v3, v7
	v_cndmask_b32_e32 v6, 0, v62, vcc
	v_fmac_f32_e32 v6, v28, v5
	v_exp_f32_e32 v5, v6
	v_or_b32_e32 v6, 18, v0
	v_cvt_f32_i32_e32 v6, v6
	ds_write2_b32 v21, v4, v3 offset0:172 offset1:188
	v_cndmask_b32_e32 v3, 0, v64, vcc
	v_ldexp_f32 v3, v5, v3
	v_mul_f32_e32 v4, v3, v12
	v_mul_f32_e32 v5, v3, v16
	v_add_u32_e32 v7, 0xa800, v1
	ds_write2_b32 v7, v4, v5 offset0:64 offset1:80
	v_mul_f32_e32 v5, v28, v6
	v_cmp_gt_f32_e32 vcc, s30, v5
	v_mul_f32_e32 v4, v3, v32
	v_mul_f32_e32 v3, v3, v8
	v_cndmask_b32_e32 v5, 0, v62, vcc
	v_fmac_f32_e32 v5, v28, v6
	v_exp_f32_e32 v5, v5
	ds_write2_b32 v7, v4, v3 offset0:96 offset1:112
	v_cndmask_b32_e32 v3, 0, v64, vcc
	v_add_u32_e32 v1, 0xac00, v1
	v_ldexp_f32 v3, v5, v3
	v_or_b32_e32 v5, 19, v0
	v_cvt_f32_i32_e32 v5, v5
	v_mul_f32_e32 v4, v3, v13
	v_mul_f32_e32 v6, v3, v17
	ds_write2_b32 v7, v4, v6 offset0:196 offset1:212
	v_mul_f32_e32 v6, v28, v5
	v_cmp_gt_f32_e32 vcc, s30, v6
	v_add_u32_e32 v0, 20, v0
	v_mul_f32_e32 v4, v3, v33
	v_cndmask_b32_e32 v6, 0, v62, vcc
	v_fmac_f32_e32 v6, v28, v5
	v_exp_f32_e32 v5, v6
	v_mul_f32_e32 v3, v3, v9
	v_cvt_f32_i32_e32 v0, v0
	ds_write2_b32 v7, v4, v3 offset0:228 offset1:244
	v_cndmask_b32_e32 v3, 0, v64, vcc
	v_ldexp_f32 v3, v5, v3
	v_mul_f32_e32 v4, v3, v14
	v_mul_f32_e32 v5, v3, v18
	ds_write2_b32 v1, v4, v5 offset0:72 offset1:88
	v_mul_f32_e32 v5, v28, v0
	v_cmp_gt_f32_e32 vcc, s30, v5
	v_mul_f32_e32 v4, v3, v34
	v_mul_f32_e32 v3, v3, v10
	v_cndmask_b32_e32 v5, 0, v62, vcc
	v_fmac_f32_e32 v5, v28, v0
	v_exp_f32_e32 v0, v5
	ds_write2_b32 v1, v4, v3 offset0:104 offset1:120
	v_cndmask_b32_e32 v3, 0, v64, vcc
	v_and_b32_e32 v10, 0x60, v2
	v_ldexp_f32 v0, v0, v3
	v_mul_f32_e32 v3, v0, v15
	v_mul_f32_e32 v4, v0, v19
	ds_write2_b32 v1, v3, v4 offset0:204 offset1:220
	v_add_u32_e32 v4, s45, v66
	v_mul_f32_e32 v3, v0, v35
	v_mul_f32_e32 v0, v0, v11
	v_ashrrev_i32_e32 v5, 31, v4
	ds_write2_b32 v1, v3, v0 offset0:236 offset1:252
	v_lshlrev_b64 v[0:1], 11, v[4:5]
	v_lshl_add_u64 v[6:7], s[10:11], 0, v[0:1]
	v_lshl_add_u64 v[0:1], v[6:7], 0, s[18:19]
	v_lshlrev_b32_e32 v28, 1, v10
	v_lshl_add_u64 v[8:9], v[0:1], 0, v[28:29]
	v_mad_i64_i32 v[4:5], s[26:27], v4, s42, v[6:7]
	v_add_co_u32_e32 v34, vcc, s41, v8
	v_lshl_add_u64 v[4:5], v[4:5], 0, s[18:19]
	s_nop 0
	v_addc_co_u32_e32 v35, vcc, 0, v9, vcc
	v_lshl_add_u64 v[12:13], v[4:5], 0, v[28:29]
	v_lshl_add_u64 v[32:33], v[8:9], 0, s[22:23]
	v_add_co_u32_e32 v4, vcc, s43, v12
	s_waitcnt lgkmcnt(0)
	s_barrier
; #define LAS __attribute__((address_space(3)))
; __device__ __forceinline__ float lo_bf(unsigned x) { return __uint_as_float(x << 16); }
; __device__ __forceinline__ float hi_bf(unsigned x) { return __uint_as_float(x & 0xffff0000u); }
; __device__ __forceinline__ float quad_sum(float v) { v += dppf<0xB1>(v); v += dppf<0x4E>(v); return v; }
; __device__ __forceinline__ void ret_unit_c(PR P, LAS unsigned char* lds, const int bh, const int n, const int wv) {
;     ...
;     { const int i = tid >> 2, part = tid & 3; float yv[32]; float s = 0.f;
;       bf16_t* yo = Y + (size_t)(row0 + i) * 1024 + 512 + h * 128 + part * 32;
; #pragma unroll
;       for (int x = 0; x < 4; ++x) { const u32x4 y1 = *(const u32x4*)(yo + x * 8); const f32x4 ta = *(const LAS f32x4*)(YST + i * 132 + part * 32 + x * 8), tb = *(const LAS f32x4*)(YST + i * 132 + part * 32 + x * 8 + 4);
;           yv[x * 8 + 0] = ta[0] + lo_bf(y1.x); yv[x * 8 + 1] = ta[1] + hi_bf(y1.x); yv[x * 8 + 2] = ta[2] + lo_bf(y1.y); yv[x * 8 + 3] = ta[3] + hi_bf(y1.y);
;           yv[x * 8 + 4] = tb[0] + lo_bf(y1.z); yv[x * 8 + 5] = tb[1] + hi_bf(y1.z); yv[x * 8 + 6] = tb[2] + lo_bf(y1.w); yv[x * 8 + 7] = tb[3] + hi_bf(y1.w); }
; #pragma unroll
;       for (int x = 0; x < 32; ++x) s += yv[x];
;       s = quad_sum(s); const float mean = s * (1.0f / 128.0f); float s2 = 0.f;
; #pragma unroll
;       for (int x = 0; x < 32; ++x) { yv[x] -= mean; s2 += yv[x] * yv[x]; }
;       s2 = quad_sum(s2); const float rstd = rsqrtf(s2 * (1.0f / 128.0f) + 1e-5f);
;       const bf16_t* gp = PS + (size_t)(row0 + i) * NCOLS + 1792 + 1536 + h * 128 + part * 32; const float* gw = P.gn_w + h * 128 + part * 32;
; #pragma unroll
;       for (int x = 0; x < 4; ++x) { const u32x4 g4 = *(const u32x4*)(gp + x * 8); const float4 w0 = *(const float4*)(gw + x * 8), w1 = *(const float4*)(gw + x * 8 + 4);
;           const float gg[8] = {lo_bf(g4.x), hi_bf(g4.x), lo_bf(g4.y), hi_bf(g4.y), lo_bf(g4.z), hi_bf(g4.z), lo_bf(g4.w), hi_bf(g4.w)}; const float ww[8] = {w0.x, w0.y, w0.z, w0.w, w1.x, w1.y, w1.z, w1.w};
;           float o[8];
; #pragma unroll
;           for (int z = 0; z < 8; ++z) o[z] = yv[x * 8 + z] * rstd * ww[z] * (gg[z] * __builtin_amdgcn_rcpf(1.0f + __expf(-gg[z])));
	global_load_dwordx4 v[0:3], v[32:33], off offset:48
	v_addc_co_u32_e32 v5, vcc, 0, v13, vcc
	global_load_dwordx4 v[58:61], v[4:5], off offset:512
	global_load_dwordx4 v[52:55], v[34:35], off offset:3072
	v_mul_lo_u32 v4, v66, s40
	global_load_dwordx4 v[20:23], v[32:33], off offset:32
	global_load_dwordx4 v[66:69], v[32:33], off offset:16
	v_lshlrev_b32_e32 v28, 2, v10
	v_add3_u32 v8, 0, v4, v28
	ds_read_b128 v[70:73], v8 offset:34816
	ds_read_b128 v[44:47], v8 offset:34832
	ds_read_b128 v[74:77], v8 offset:34848
	ds_read_b128 v[78:81], v8 offset:34864
	ds_read_b128 v[4:7], v8 offset:34912
	ds_read_b128 v[24:27], v8 offset:34880
	ds_read_b128 v[82:85], v8 offset:34896
	ds_read_b128 v[8:11], v8 offset:34928
	s_lshl_b32 s18, s44, 9
	s_add_u32 s26, s12, s18
	s_addc_u32 s27, s13, 0
	s_addk_i32 s28, 0x80
	s_cmpk_eq_i32 s28, 0x180
	s_waitcnt vmcnt(4)
	v_and_b32_e32 v15, 0xffff0000, v0
	v_lshlrev_b32_e32 v14, 16, v0
	s_waitcnt lgkmcnt(3)
	v_pk_add_f32 v[40:41], v[4:5], v[14:15]
	v_and_b32_e32 v5, 0xffff0000, v1
	v_lshlrev_b32_e32 v4, 16, v1
	v_and_b32_e32 v1, 0xffff0000, v2
	v_lshlrev_b32_e32 v0, 16, v2
	s_waitcnt vmcnt(3)
	v_lshlrev_b32_e32 v38, 16, v60
	s_waitcnt lgkmcnt(0)
	v_pk_add_f32 v[48:49], v[8:9], v[0:1]
	v_lshl_add_u64 v[8:9], v[12:13], 0, s[24:25]
	s_waitcnt vmcnt(2)
	v_lshlrev_b32_e32 v12, 16, v55
	v_and_b32_e32 v13, 0xffff0000, v55
	v_and_b32_e32 v39, 0xffff0000, v60
	v_mul_f32_e32 v37, 0xbfb8aa3b, v38
	v_pk_add_f32 v[56:57], v[46:47], v[12:13]
	v_exp_f32_e32 v46, v37
	v_mul_f32_e32 v37, 0xbfb8aa3b, v39
	v_exp_f32_e32 v47, v37
	v_lshlrev_b32_e32 v36, 16, v61
	v_add_f32_e32 v46, 1.0, v46
	v_rcp_f32_e32 v46, v46
	v_add_f32_e32 v47, 1.0, v47
	v_rcp_f32_e32 v47, v47
	v_and_b32_e32 v37, 0xffff0000, v61
	v_lshlrev_b32_e32 v60, 16, v54
	v_and_b32_e32 v61, 0xffff0000, v54
	v_pk_add_f32 v[60:61], v[44:45], v[60:61]
	v_lshlrev_b32_e32 v44, 16, v59
	v_and_b32_e32 v45, 0xffff0000, v59
	v_pk_mul_f32 v[38:39], v[46:47], v[38:39]
	v_lshlrev_b32_e32 v46, 16, v53
	v_and_b32_e32 v47, 0xffff0000, v53
	v_mul_f32_e32 v53, 0xbfb8aa3b, v44
	v_mul_f32_e32 v54, 0xbfb8aa3b, v45
	v_exp_f32_e32 v53, v53
	v_exp_f32_e32 v54, v54
	v_pk_add_f32 v[72:73], v[72:73], v[46:47]
	v_and_b32_e32 v55, 0xffff0000, v52
	v_add_f32_e32 v46, 1.0, v53
	v_add_f32_e32 v47, 1.0, v54
	v_lshlrev_b32_e32 v54, 16, v52
	v_lshlrev_b32_e32 v52, 16, v58
	v_and_b32_e32 v53, 0xffff0000, v58
	v_pk_add_f32 v[70:71], v[70:71], v[54:55]
	v_mul_f32_e32 v55, 0xbfb8aa3b, v52
	v_mul_f32_e32 v58, 0xbfb8aa3b, v53
	v_exp_f32_e32 v55, v55
	v_exp_f32_e32 v58, v58
	v_add_f32_e32 v54, 0, v70
	v_add_f32_e32 v59, v71, v54
	v_add_f32_e32 v54, 1.0, v55
	v_add_f32_e32 v55, 1.0, v58
	v_add_f32_e32 v58, v72, v59
	v_mul_f32_e32 v59, 0xbfb8aa3b, v36
	v_mul_f32_e32 v86, 0xbfb8aa3b, v37
	v_add_f32_e32 v58, v73, v58
	v_exp_f32_e32 v59, v59
	v_exp_f32_e32 v86, v86
	v_add_f32_e32 v58, v60, v58
	v_and_b32_e32 v1, 0xffff0000, v3
	v_lshlrev_b32_e32 v0, 16, v3
	v_add_f32_e32 v58, v61, v58
	v_pk_add_f32 v[42:43], v[6:7], v[4:5]
	v_pk_add_f32 v[50:51], v[10:11], v[0:1]
	global_load_dwordx4 v[0:3], v[8:9], off offset:48
	global_load_dwordx4 v[4:7], v[8:9], off offset:32
	s_nop 0
	global_load_dwordx4 v[8:11], v[8:9], off offset:16
	s_nop 0
	s_nop 1
	v_mov_b32_e32 v12, v232
	v_mov_b32_e32 v13, v233
	v_mov_b32_e32 v14, v234
	v_mov_b32_e32 v15, v235
	s_nop 1
	v_mov_b32_e32 v16, v228
	v_mov_b32_e32 v17, v229
	v_mov_b32_e32 v18, v230
	v_mov_b32_e32 v19, v231
	v_add_f32_e32 v58, v56, v58
	v_add_f32_e32 v88, v57, v58
	v_add_f32_e32 v58, 1.0, v59
	v_add_f32_e32 v59, 1.0, v86
	s_waitcnt vmcnt(3)
	v_lshlrev_b32_e32 v86, 16, v69
	v_and_b32_e32 v87, 0xffff0000, v69
	v_pk_add_f32 v[80:81], v[80:81], v[86:87]
	v_lshlrev_b32_e32 v86, 16, v68
	v_and_b32_e32 v87, 0xffff0000, v68
	v_pk_add_f32 v[68:69], v[78:79], v[86:87]
	v_lshlrev_b32_e32 v78, 16, v67
	v_and_b32_e32 v79, 0xffff0000, v67
	v_pk_add_f32 v[76:77], v[76:77], v[78:79]
	v_lshlrev_b32_e32 v78, 16, v66
	v_and_b32_e32 v79, 0xffff0000, v66
	v_pk_add_f32 v[66:67], v[74:75], v[78:79]
	v_lshlrev_b32_e32 v78, 16, v22
	v_add_f32_e32 v74, v66, v88
	v_add_f32_e32 v74, v67, v74
	v_add_f32_e32 v74, v76, v74
	v_add_f32_e32 v74, v77, v74
	v_add_f32_e32 v74, v68, v74
	v_add_f32_e32 v74, v69, v74
	v_add_f32_e32 v74, v80, v74
	v_and_b32_e32 v79, 0xffff0000, v22
	v_add_f32_e32 v86, v81, v74
	v_lshlrev_b32_e32 v74, 16, v23
	v_and_b32_e32 v75, 0xffff0000, v23
	v_pk_add_f32 v[22:23], v[82:83], v[78:79]
	v_lshlrev_b32_e32 v78, 16, v21
	v_and_b32_e32 v79, 0xffff0000, v21
	v_pk_add_f32 v[26:27], v[26:27], v[78:79]
	v_lshlrev_b32_e32 v78, 16, v20
	v_and_b32_e32 v79, 0xffff0000, v20
	v_pk_add_f32 v[20:21], v[24:25], v[78:79]
	v_pk_add_f32 v[74:75], v[84:85], v[74:75]
	v_add_f32_e32 v24, v20, v86
	v_add_f32_e32 v24, v21, v24
	v_add_f32_e32 v24, v26, v24
	v_add_f32_e32 v24, v27, v24
	v_add_f32_e32 v24, v22, v24
	v_add_f32_e32 v24, v23, v24
	v_add_f32_e32 v24, v74, v24
	v_add_f32_e32 v24, v75, v24
	v_add_f32_e32 v24, v40, v24
	v_add_f32_e32 v24, v41, v24
	v_add_f32_e32 v24, v42, v24
	v_add_f32_e32 v24, v43, v24
	v_add_f32_e32 v24, v48, v24
	v_add_f32_e32 v24, v49, v24
	v_add_f32_e32 v24, v50, v24
	v_add_f32_e32 v24, v51, v24
	v_rcp_f32_e32 v46, v46
	v_rcp_f32_e32 v47, v47
	v_add_f32_dpp v24, v24, v24 quad_perm:[1,0,3,2] row_mask:0xf bank_mask:0xf bound_ctrl:1
	v_rcp_f32_e32 v54, v54
	v_rcp_f32_e32 v55, v55
	v_add_f32_dpp v24, v24, v24 quad_perm:[2,3,0,1] row_mask:0xf bank_mask:0xf bound_ctrl:1
	v_mul_f32_e32 v78, 0x3c000000, v24
	v_pk_add_f32 v[70:71], v[70:71], v[78:79] op_sel_hi:[1,0] neg_lo:[0,1] neg_hi:[0,1]
	v_pk_add_f32 v[72:73], v[72:73], v[78:79] op_sel_hi:[1,0] neg_lo:[0,1] neg_hi:[0,1]
; __device__ __forceinline__ unsigned cvt_pk_bf16(float lo, float hi) { const f32x2_t v = {lo, hi}; const bf16x2_t b = __builtin_convertvector(v, bf16x2_t); return __builtin_bit_cast(unsigned, b); }
; __device__ __forceinline__ float lo_bf(unsigned x) { return __uint_as_float(x << 16); }
; __device__ __forceinline__ float hi_bf(unsigned x) { return __uint_as_float(x & 0xffff0000u); }
; __device__ __forceinline__ float quad_sum(float v) { v += dppf<0xB1>(v); v += dppf<0x4E>(v); return v; }
; __device__ __forceinline__ void ret_unit_c(PR P, LAS unsigned char* lds, const int bh, const int n, const int wv) {
;     ...
;       s = quad_sum(s); const float mean = s * (1.0f / 128.0f); float s2 = 0.f;
; #pragma unroll
;       for (int x = 0; x < 32; ++x) { yv[x] -= mean; s2 += yv[x] * yv[x]; }
;       s2 = quad_sum(s2); const float rstd = rsqrtf(s2 * (1.0f / 128.0f) + 1e-5f);
;       const bf16_t* gp = PS + (size_t)(row0 + i) * NCOLS + 1792 + 1536 + h * 128 + part * 32; const float* gw = P.gn_w + h * 128 + part * 32;
; #pragma unroll
;       for (int x = 0; x < 4; ++x) { const u32x4 g4 = *(const u32x4*)(gp + x * 8); const float4 w0 = *(const float4*)(gw + x * 8), w1 = *(const float4*)(gw + x * 8 + 4);
;           const float gg[8] = {lo_bf(g4.x), hi_bf(g4.x), lo_bf(g4.y), hi_bf(g4.y), lo_bf(g4.z), hi_bf(g4.z), lo_bf(g4.w), hi_bf(g4.w)}; const float ww[8] = {w0.x, w0.y, w0.z, w0.w, w1.x, w1.y, w1.z, w1.w};
;           float o[8];
; #pragma unroll
;           for (int z = 0; z < 8; ++z) o[z] = yv[x * 8 + z] * rstd * ww[z] * (gg[z] * __builtin_amdgcn_rcpf(1.0f + __expf(-gg[z])));
;           u32x4 w; w.x = pg8::cvt_pk_bf16(o[0], o[1]); w.y = pg8::cvt_pk_bf16(o[2], o[3]); w.z = pg8::cvt_pk_bf16(o[4], o[5]); w.w = pg8::cvt_pk_bf16(o[6], o[7]);
;           *(u32x4*)(yo + x * 8) = w; } }
	v_pk_mul_f32 v[82:83], v[70:71], v[70:71]
	v_pk_mul_f32 v[84:85], v[72:73], v[72:73]
	v_add_f32_e32 v82, v82, v83
	v_pk_add_f32 v[60:61], v[60:61], v[78:79] op_sel_hi:[1,0] neg_lo:[0,1] neg_hi:[0,1]
	v_add_f32_e32 v82, v84, v82
	v_pk_mul_f32 v[86:87], v[60:61], v[60:61]
	v_add_f32_e32 v82, v85, v82
	v_pk_add_f32 v[56:57], v[56:57], v[78:79] op_sel_hi:[1,0] neg_lo:[0,1] neg_hi:[0,1]
	v_add_f32_e32 v82, v86, v82
	v_pk_mul_f32 v[88:89], v[56:57], v[56:57]
	v_add_f32_e32 v82, v87, v82
	v_pk_add_f32 v[66:67], v[66:67], v[78:79] op_sel_hi:[1,0] neg_lo:[0,1] neg_hi:[0,1]
	v_add_f32_e32 v82, v88, v82
	v_pk_mul_f32 v[90:91], v[66:67], v[66:67]
	v_add_f32_e32 v82, v89, v82
	v_pk_add_f32 v[76:77], v[76:77], v[78:79] op_sel_hi:[1,0] neg_lo:[0,1] neg_hi:[0,1]
	v_add_f32_e32 v82, v90, v82
	v_pk_mul_f32 v[92:93], v[76:77], v[76:77]
	v_add_f32_e32 v82, v91, v82
	v_pk_add_f32 v[68:69], v[68:69], v[78:79] op_sel_hi:[1,0] neg_lo:[0,1] neg_hi:[0,1]
	v_add_f32_e32 v82, v92, v82
	v_pk_mul_f32 v[94:95], v[68:69], v[68:69]
	v_add_f32_e32 v82, v93, v82
	v_pk_add_f32 v[80:81], v[80:81], v[78:79] op_sel_hi:[1,0] neg_lo:[0,1] neg_hi:[0,1]
	v_add_f32_e32 v82, v94, v82
	v_pk_mul_f32 v[96:97], v[80:81], v[80:81]
	v_add_f32_e32 v82, v95, v82
	v_pk_add_f32 v[98:99], v[20:21], v[78:79] op_sel_hi:[1,0] neg_lo:[0,1] neg_hi:[0,1]
	v_add_f32_e32 v82, v96, v82
	v_pk_mul_f32 v[100:101], v[98:99], v[98:99]
	v_add_f32_e32 v82, v97, v82
	v_pk_add_f32 v[26:27], v[26:27], v[78:79] op_sel_hi:[1,0] neg_lo:[0,1] neg_hi:[0,1]
	v_add_f32_e32 v82, v100, v82
	v_pk_mul_f32 v[102:103], v[26:27], v[26:27]
	v_add_f32_e32 v82, v101, v82
	v_pk_add_f32 v[104:105], v[22:23], v[78:79] op_sel_hi:[1,0] neg_lo:[0,1] neg_hi:[0,1]
	v_add_f32_e32 v82, v102, v82
	v_pk_mul_f32 v[106:107], v[104:105], v[104:105]
	v_add_f32_e32 v82, v103, v82
	v_pk_add_f32 v[74:75], v[74:75], v[78:79] op_sel_hi:[1,0] neg_lo:[0,1] neg_hi:[0,1]
	v_add_f32_e32 v82, v106, v82
	v_pk_mul_f32 v[108:109], v[74:75], v[74:75]
	v_add_f32_e32 v82, v107, v82
	v_pk_add_f32 v[40:41], v[40:41], v[78:79] op_sel_hi:[1,0] neg_lo:[0,1] neg_hi:[0,1]
	v_add_f32_e32 v82, v108, v82
	v_pk_add_f32 v[22:23], v[48:49], v[78:79] op_sel_hi:[1,0] neg_lo:[0,1] neg_hi:[0,1]
	v_pk_add_f32 v[20:21], v[50:51], v[78:79] op_sel_hi:[1,0] neg_lo:[0,1] neg_hi:[0,1]
	v_pk_add_f32 v[24:25], v[42:43], v[78:79] op_sel_hi:[1,0] neg_lo:[0,1] neg_hi:[0,1]
	v_pk_mul_f32 v[78:79], v[40:41], v[40:41]
	v_add_f32_e32 v82, v109, v82
	v_add_f32_e32 v78, v78, v82
	v_pk_mul_f32 v[42:43], v[24:25], v[24:25]
	v_add_f32_e32 v78, v79, v78
	v_add_f32_e32 v42, v42, v78
	v_pk_mul_f32 v[48:49], v[22:23], v[22:23]
	v_add_f32_e32 v42, v43, v42
	v_add_f32_e32 v42, v48, v42
	v_pk_mul_f32 v[50:51], v[20:21], v[20:21]
	v_add_f32_e32 v42, v49, v42
	v_add_f32_e32 v42, v50, v42
	v_add_f32_e32 v42, v51, v42
	v_rcp_f32_e32 v58, v58
	v_rcp_f32_e32 v59, v59
	v_add_f32_dpp v42, v42, v42 quad_perm:[1,0,3,2] row_mask:0xf bank_mask:0xf bound_ctrl:1
	v_pk_mul_f32 v[36:37], v[58:59], v[36:37]
	s_nop 0
	v_add_f32_dpp v42, v42, v42 quad_perm:[2,3,0,1] row_mask:0xf bank_mask:0xf bound_ctrl:1
	v_fmamk_f32 v42, v42, 0x3c000000, v65
	v_mul_f32_e32 v43, 0x4b800000, v42
	v_cmp_gt_f32_e32 vcc, s37, v42
	s_nop 1
	v_cndmask_b32_e32 v42, v42, v43, vcc
	v_rsq_f32_e32 v48, v42
	v_pk_mul_f32 v[42:43], v[46:47], v[44:45]
	v_pk_mul_f32 v[44:45], v[54:55], v[52:53]
	v_mul_f32_e32 v46, 0x45800000, v48
	v_cndmask_b32_e32 v46, v48, v46, vcc
	v_pk_mul_f32 v[48:49], v[70:71], v[46:47] op_sel_hi:[1,0]
	s_waitcnt vmcnt(0)
	v_pk_mul_f32 v[16:17], v[16:17], v[48:49]
	s_nop 0
	v_pk_mul_f32 v[16:17], v[44:45], v[16:17]
	v_pk_mul_f32 v[44:45], v[72:73], v[46:47] op_sel_hi:[1,0]
	s_nop 0
	v_pk_mul_f32 v[18:19], v[18:19], v[44:45]
	v_and_b32_e32 v45, 0xffff0000, v8
	v_pk_mul_f32 v[18:19], v[42:43], v[18:19]
	v_pk_mul_f32 v[42:43], v[60:61], v[46:47] op_sel_hi:[1,0]
	v_lshlrev_b32_e32 v44, 16, v8
	v_pk_mul_f32 v[12:13], v[12:13], v[42:43]
	v_mul_f32_e32 v8, 0xbfb8aa3b, v44
	v_pk_mul_f32 v[38:39], v[38:39], v[12:13]
	v_pk_mul_f32 v[12:13], v[56:57], v[46:47] op_sel_hi:[1,0]
	v_exp_f32_e32 v8, v8
	v_pk_mul_f32 v[12:13], v[14:15], v[12:13]
	v_cvt_pk_bf16_f32 v14, v38, v39
	v_pk_mul_f32 v[36:37], v[36:37], v[12:13]
	v_cvt_pk_bf16_f32 v12, v16, v17
	v_cvt_pk_bf16_f32 v13, v18, v19
	v_cvt_pk_bf16_f32 v15, v36, v37
	global_store_dwordx4 v[34:35], v[12:15], off offset:3072
	s_nop 1
	v_mov_b32_e32 v12, v236
	v_mov_b32_e32 v13, v237
	v_mov_b32_e32 v14, v238
	v_mov_b32_e32 v15, v239
	s_nop 0
	s_nop 1
	v_mov_b32_e32 v16, v240
	v_mov_b32_e32 v17, v241
	v_mov_b32_e32 v18, v242
	v_mov_b32_e32 v19, v243
	v_and_b32_e32 v37, 0xffff0000, v10
	v_mul_f32_e32 v35, 0xbfb8aa3b, v37
	v_exp_f32_e32 v38, v35
	v_lshlrev_b32_e32 v34, 16, v11
	v_and_b32_e32 v35, 0xffff0000, v11
	v_and_b32_e32 v39, 0xffff0000, v9
	v_add_f32_e32 v11, 1.0, v38
	v_lshlrev_b32_e32 v38, 16, v9
	v_mul_f32_e32 v9, 0xbfb8aa3b, v38
	v_exp_f32_e32 v9, v9
	v_mul_f32_e32 v42, 0xbfb8aa3b, v39
	v_exp_f32_e32 v43, v42
	v_lshlrev_b32_e32 v36, 16, v10
	v_add_f32_e32 v9, 1.0, v9
	v_rcp_f32_e32 v42, v9
	v_add_f32_e32 v9, 1.0, v43
	v_mul_f32_e32 v43, 0xbfb8aa3b, v45
	v_exp_f32_e32 v47, v43
	v_mul_f32_e32 v10, 0xbfb8aa3b, v36
	v_exp_f32_e32 v10, v10
	v_rcp_f32_e32 v43, v9
	v_add_f32_e32 v9, 1.0, v47
	v_mul_f32_e32 v47, 0xbfb8aa3b, v34
	v_exp_f32_e32 v47, v47
	v_mul_f32_e32 v48, 0xbfb8aa3b, v35
	v_add_f32_e32 v10, 1.0, v10
	v_exp_f32_e32 v49, v48
	v_rcp_f32_e32 v10, v10
	v_rcp_f32_e32 v11, v11
	v_add_f32_e32 v8, 1.0, v8
	v_rcp_f32_e32 v8, v8
	v_rcp_f32_e32 v9, v9
	v_add_f32_e32 v47, 1.0, v47
	v_rcp_f32_e32 v48, v47
	v_add_f32_e32 v47, 1.0, v49
	v_pk_mul_f32 v[10:11], v[10:11], v[36:37]
; __device__ __forceinline__ unsigned cvt_pk_bf16(float lo, float hi) { const f32x2_t v = {lo, hi}; const bf16x2_t b = __builtin_convertvector(v, bf16x2_t); return __builtin_bit_cast(unsigned, b); }
; __device__ __forceinline__ float lo_bf(unsigned x) { return __uint_as_float(x << 16); }
; __device__ __forceinline__ float hi_bf(unsigned x) { return __uint_as_float(x & 0xffff0000u); }
; __device__ __forceinline__ void ret_unit_c(PR P, LAS unsigned char* lds, const int bh, const int n, const int wv) {
;     ...
; #pragma unroll
;       for (int x = 0; x < 4; ++x) { const u32x4 g4 = *(const u32x4*)(gp + x * 8); const float4 w0 = *(const float4*)(gw + x * 8), w1 = *(const float4*)(gw + x * 8 + 4);
;           const float gg[8] = {lo_bf(g4.x), hi_bf(g4.x), lo_bf(g4.y), hi_bf(g4.y), lo_bf(g4.z), hi_bf(g4.z), lo_bf(g4.w), hi_bf(g4.w)}; const float ww[8] = {w0.x, w0.y, w0.z, w0.w, w1.x, w1.y, w1.z, w1.w};
;           float o[8];
; #pragma unroll
;           for (int z = 0; z < 8; ++z) o[z] = yv[x * 8 + z] * rstd * ww[z] * (gg[z] * __builtin_amdgcn_rcpf(1.0f + __expf(-gg[z])));
;           u32x4 w; w.x = pg8::cvt_pk_bf16(o[0], o[1]); w.y = pg8::cvt_pk_bf16(o[2], o[3]); w.z = pg8::cvt_pk_bf16(o[4], o[5]); w.w = pg8::cvt_pk_bf16(o[6], o[7]);
;           *(u32x4*)(yo + x * 8) = w; } }
;     __syncthreads();
	v_pk_mul_f32 v[36:37], v[42:43], v[38:39]
	v_pk_mul_f32 v[38:39], v[66:67], v[46:47] op_sel_hi:[1,0]
	v_pk_mul_f32 v[8:9], v[8:9], v[44:45]
	v_rcp_f32_e32 v49, v47
	v_pk_mul_f32 v[12:13], v[12:13], v[38:39]
	s_nop 0
	v_pk_mul_f32 v[8:9], v[8:9], v[12:13]
	v_pk_mul_f32 v[12:13], v[76:77], v[46:47] op_sel_hi:[1,0]
	v_pk_mul_f32 v[34:35], v[48:49], v[34:35]
	v_pk_mul_f32 v[12:13], v[14:15], v[12:13]
	v_pk_mul_f32 v[14:15], v[68:69], v[46:47] op_sel_hi:[1,0]
	v_pk_mul_f32 v[12:13], v[36:37], v[12:13]
	v_pk_mul_f32 v[14:15], v[16:17], v[14:15]
	v_cvt_pk_bf16_f32 v8, v8, v9
	v_pk_mul_f32 v[10:11], v[10:11], v[14:15]
	v_pk_mul_f32 v[14:15], v[80:81], v[46:47] op_sel_hi:[1,0]
	v_cvt_pk_bf16_f32 v9, v12, v13
	v_pk_mul_f32 v[14:15], v[18:19], v[14:15]
	v_cvt_pk_bf16_f32 v10, v10, v11
	v_pk_mul_f32 v[14:15], v[34:35], v[14:15]
	v_and_b32_e32 v19, 0xffff0000, v6
	v_cvt_pk_bf16_f32 v11, v14, v15
	global_store_dwordx4 v[32:33], v[8:11], off offset:16
	s_nop 1
	v_mov_b32_e32 v8, v244
	v_mov_b32_e32 v9, v245
	v_mov_b32_e32 v10, v246
	v_mov_b32_e32 v11, v247
	s_nop 0
	s_nop 1
	v_mov_b32_e32 v12, v248
	v_mov_b32_e32 v13, v249
	v_mov_b32_e32 v14, v250
	v_mov_b32_e32 v15, v251
	v_mul_f32_e32 v17, 0xbfb8aa3b, v19
	v_exp_f32_e32 v34, v17
	v_lshlrev_b32_e32 v16, 16, v7
	v_and_b32_e32 v17, 0xffff0000, v7
	v_and_b32_e32 v35, 0xffff0000, v5
	v_add_f32_e32 v7, 1.0, v34
	v_lshlrev_b32_e32 v34, 16, v5
	v_mul_f32_e32 v5, 0xbfb8aa3b, v34
	v_exp_f32_e32 v5, v5
	v_mul_f32_e32 v36, 0xbfb8aa3b, v35
	v_exp_f32_e32 v37, v36
	v_lshlrev_b32_e32 v18, 16, v6
	v_mul_f32_e32 v6, 0xbfb8aa3b, v18
	v_add_f32_e32 v5, 1.0, v5
	v_lshlrev_b32_e32 v38, 16, v4
	v_and_b32_e32 v39, 0xffff0000, v4
	v_exp_f32_e32 v6, v6
	v_rcp_f32_e32 v36, v5
	v_add_f32_e32 v5, 1.0, v37
	v_mul_f32_e32 v4, 0xbfb8aa3b, v38
	v_mul_f32_e32 v37, 0xbfb8aa3b, v39
	v_exp_f32_e32 v4, v4
	v_exp_f32_e32 v42, v37
	v_add_f32_e32 v6, 1.0, v6
	v_rcp_f32_e32 v6, v6
	v_rcp_f32_e32 v7, v7
	v_rcp_f32_e32 v37, v5
	v_add_f32_e32 v4, 1.0, v4
	v_add_f32_e32 v5, 1.0, v42
	v_mul_f32_e32 v42, 0xbfb8aa3b, v16
	v_mul_f32_e32 v43, 0xbfb8aa3b, v17
	v_rcp_f32_e32 v4, v4
	v_exp_f32_e32 v42, v42
	v_exp_f32_e32 v43, v43
	v_rcp_f32_e32 v5, v5
	v_pk_mul_f32 v[6:7], v[6:7], v[18:19]
	v_pk_mul_f32 v[18:19], v[36:37], v[34:35]
	v_pk_mul_f32 v[34:35], v[98:99], v[46:47] op_sel_hi:[1,0]
	v_add_f32_e32 v42, 1.0, v42
	v_add_f32_e32 v43, 1.0, v43
	v_pk_mul_f32 v[4:5], v[4:5], v[38:39]
	v_rcp_f32_e32 v42, v42
	v_rcp_f32_e32 v43, v43
	v_pk_mul_f32 v[8:9], v[8:9], v[34:35]
	s_nop 0
	v_pk_mul_f32 v[4:5], v[4:5], v[8:9]
	v_pk_mul_f32 v[8:9], v[26:27], v[46:47] op_sel_hi:[1,0]
	v_pk_mul_f32 v[16:17], v[42:43], v[16:17]
	v_pk_mul_f32 v[8:9], v[10:11], v[8:9]
	v_pk_mul_f32 v[10:11], v[104:105], v[46:47] op_sel_hi:[1,0]
	v_pk_mul_f32 v[8:9], v[18:19], v[8:9]
	v_pk_mul_f32 v[10:11], v[12:13], v[10:11]
	v_cvt_pk_bf16_f32 v4, v4, v5
	v_pk_mul_f32 v[6:7], v[6:7], v[10:11]
	v_pk_mul_f32 v[10:11], v[74:75], v[46:47] op_sel_hi:[1,0]
	v_cvt_pk_bf16_f32 v5, v8, v9
	v_pk_mul_f32 v[10:11], v[14:15], v[10:11]
	v_cvt_pk_bf16_f32 v6, v6, v7
	v_pk_mul_f32 v[10:11], v[16:17], v[10:11]
	v_lshlrev_b32_e32 v12, 16, v0
	v_cvt_pk_bf16_f32 v7, v10, v11
	global_store_dwordx4 v[32:33], v[4:7], off offset:32
	s_nop 1
	v_mov_b32_e32 v4, v192
	v_mov_b32_e32 v5, v193
	v_mov_b32_e32 v6, v194
	v_mov_b32_e32 v7, v195
	s_nop 0
	s_nop 1
	v_mov_b32_e32 v8, v196
	v_mov_b32_e32 v9, v197
	v_mov_b32_e32 v10, v198
	v_mov_b32_e32 v11, v199
	v_and_b32_e32 v13, 0xffff0000, v0
	v_mul_f32_e32 v0, 0xbfb8aa3b, v12
	v_exp_f32_e32 v0, v0
	v_mul_f32_e32 v14, 0xbfb8aa3b, v13
	v_exp_f32_e32 v15, v14
	v_add_f32_e32 v0, 1.0, v0
	v_rcp_f32_e32 v14, v0
	v_add_f32_e32 v0, 1.0, v15
	v_rcp_f32_e32 v15, v0
	v_lshlrev_b32_e32 v0, 16, v1
	v_and_b32_e32 v1, 0xffff0000, v1
	v_pk_mul_f32 v[12:13], v[14:15], v[12:13]
	v_mul_f32_e32 v14, 0xbfb8aa3b, v0
	v_exp_f32_e32 v16, v14
	v_pk_mul_f32 v[14:15], v[40:41], v[46:47] op_sel_hi:[1,0]
	v_pk_mul_f32 v[4:5], v[4:5], v[14:15]
	s_nop 0
	v_pk_mul_f32 v[4:5], v[12:13], v[4:5]
	v_mul_f32_e32 v13, 0xbfb8aa3b, v1
	v_exp_f32_e32 v13, v13
	v_add_f32_e32 v12, 1.0, v16
	v_rcp_f32_e32 v12, v12
	v_pk_mul_f32 v[14:15], v[24:25], v[46:47] op_sel_hi:[1,0]
	v_add_f32_e32 v13, 1.0, v13
	v_rcp_f32_e32 v13, v13
	v_pk_mul_f32 v[6:7], v[6:7], v[14:15]
	v_lshlrev_b32_e32 v14, 16, v2
	v_mul_f32_e32 v15, 0xbfb8aa3b, v14
	v_exp_f32_e32 v16, v15
	v_pk_mul_f32 v[0:1], v[12:13], v[0:1]
	v_and_b32_e32 v15, 0xffff0000, v2
	v_pk_mul_f32 v[6:7], v[0:1], v[6:7]
	v_mul_f32_e32 v1, 0xbfb8aa3b, v15
	v_exp_f32_e32 v1, v1
	v_pk_mul_f32 v[12:13], v[22:23], v[46:47] op_sel_hi:[1,0]
	v_lshlrev_b32_e32 v2, 16, v3
	v_and_b32_e32 v3, 0xffff0000, v3
	v_pk_mul_f32 v[8:9], v[8:9], v[12:13]
	v_mul_f32_e32 v12, 0xbfb8aa3b, v2
	v_mul_f32_e32 v13, 0xbfb8aa3b, v3
	v_exp_f32_e32 v12, v12
	v_exp_f32_e32 v13, v13
	v_add_f32_e32 v0, 1.0, v16
	v_add_f32_e32 v1, 1.0, v1
	v_rcp_f32_e32 v0, v0
	v_rcp_f32_e32 v1, v1
	v_add_f32_e32 v12, 1.0, v12
	v_add_f32_e32 v13, 1.0, v13
	v_rcp_f32_e32 v12, v12
	v_rcp_f32_e32 v13, v13
	v_pk_mul_f32 v[0:1], v[0:1], v[14:15]
	v_pk_mul_f32 v[2:3], v[12:13], v[2:3]
	v_pk_mul_f32 v[8:9], v[0:1], v[8:9]
	v_pk_mul_f32 v[0:1], v[20:21], v[46:47] op_sel_hi:[1,0]
	s_nop 0
	v_pk_mul_f32 v[0:1], v[10:11], v[0:1]
	s_nop 0
	v_pk_mul_f32 v[10:11], v[2:3], v[0:1]
	v_cvt_pk_bf16_f32 v0, v4, v5
	v_cvt_pk_bf16_f32 v1, v6, v7
	v_cvt_pk_bf16_f32 v2, v8, v9
	v_cvt_pk_bf16_f32 v3, v10, v11
	global_store_dwordx4 v[32:33], v[0:3], off offset:48
	s_barrier
; __device__ __forceinline__ float bf2f(unsigned b) { return __uint_as_float(b << 16); }
; __device__ __forceinline__ float quad_sum(float v) { v += dppf<0xB1>(v); v += dppf<0x4E>(v); return v; }
; __device__ __forceinline__ void ret_sample_unit(PR P, LAS float* lds, const int b, const int h, const int wv) {
;     ...
;     const float lg2 = log2f(1.0f - exp2f(-5.0f - (float)h));
;     const int row0 = MP + b * 4;
;     { const int t = (tid & 255) >> 6, f = tid & 63; const bf16_t* src = PS + (size_t)(row0 + t) * NCOLS + 1792 + h * 128;
;       if (tid < 256) { const float cs = rc[(2048 + t) * 64 + f], sn = rs[(2048 + t) * 64 + f];
;           const float q1 = bf2f(src[f]), q2 = bf2f(src[f + 64]); q[t * 128 + f] = q1 * cs - q2 * sn; q[t * 128 + f + 64] = q1 * sn + q2 * cs;
;           const float k1 = bf2f(src[512 + f]), k2 = bf2f(src[512 + f + 64]); k[t * 128 + f] = (k1 * cs - k2 * sn) * 0.08838834764831845f; k[t * 128 + f + 64] = (k1 * sn + k2 * cs) * 0.08838834764831845f; }
;       else { v[t * 128 + f] = bf2f(src[1024 + f]); v[t * 128 + f + 64] = bf2f(src[1024 + f + 64]); } }
;     __syncthreads();
;     if (wid == 0) { const int pi = lane >> 4, pj = (lane >> 2) & 3, part = lane & 3; float s = 0.f;
;         for (int d = part * 32; d < part * 32 + 32; ++d) s += q[pi * 128 + d] * k[pj * 128 + d];
;         s = quad_sum(s); if (part == 0) Pm[pi * 4 + pj] = pi >= pj ? s * exp2f(lg2 * (float)(pi - pj)) : 0.f; }
;     { const int e = tid & 127, dg = tid >> 7; const float c4 = exp2f(lg2 * 4.0f), g3 = exp2f(lg2 * 3.0f), g2_ = exp2f(lg2 * 2.0f), g1 = exp2f(lg2);
; __global__ void __launch_bounds__(512, 2) hymba_mega(Params P_unused) {
;     ...
;         for (int k = 0; k < 4; ++k) { const int u = ob + k * 128; ret_unit_c(P, lds, u >> 4, u & 15, wv); }
;         for (int u = ob; u < 2560; u += 128) { if (u < 2048) rwkv_unit<true>(P, ldsf, u >> 4, (u >> 1) & 7, u & 1, wv); else ret_sample_unit(P, ldsf, (u - 2048) >> 2, (u - 2048) & 3, wv); }
	s_cbranch_scc0 .LBB0_654
	s_cmpk_gt_i32 s2, 0xa7f
	s_cbranch_scc1 .LBB0_689
	s_add_u32 s18, s10, 0x3d44800
	s_addc_u32 s19, s11, 0
	s_add_u32 s6, s8, 0x5588000
	s_addc_u32 s7, s9, 0
	s_add_u32 s20, s10, 0xea84800
	s_addc_u32 s21, s11, 0
	s_add_u32 s22, s10, 0xda04800
	s_addc_u32 s23, s11, 0
	s_add_u32 s24, s10, 0xbae4800
	s_addc_u32 s25, s11, 0
	s_add_u32 s26, s8, 0x4588000
	s_addc_u32 s27, s9, 0
	s_and_b32 s44, s2, 3
	v_cvt_f32_ubyte0_e32 v0, s44
	v_sub_f32_e32 v0, 0xc0a00000, v0
	s_mov_b32 s45, 0xc2fc0000
	v_mov_b32_e32 v72, 0x42800000
	v_cmp_gt_f32_e32 vcc, s45, v0
	s_and_b64 s[8:9], vcc, exec
	s_cselect_b32 s8, 0xffffffc0, 0
	v_cndmask_b32_e32 v1, 0, v72, vcc
	v_add_f32_e32 v0, v0, v1
	v_exp_f32_e32 v0, v0
	s_mov_b32 s46, 0x800000
	v_mov_b32_e32 v1, 0x42000000
	s_mov_b32 s29, 0
	v_ldexp_f32 v0, v0, s8
	v_sub_f32_e32 v0, 1.0, v0
	v_cmp_gt_f32_e32 vcc, s46, v0
	s_and_b64 s[8:9], vcc, exec
	s_cselect_b32 s8, 32, 0
	v_ldexp_f32 v0, v0, s8
	v_log_f32_e32 v0, v0
	v_cndmask_b32_e32 v1, 0, v1, vcc
	s_lshl_b32 s47, s44, 7
	s_movk_i32 s57, 0xf00
	v_sub_f32_e32 v73, v0, v1
	v_add_f32_e32 v2, v73, v73
	v_cmp_gt_f32_e32 vcc, s45, v2
	v_mul_f32_e32 v0, 4.0, v73
	s_and_b64 s[8:9], vcc, exec
	v_cndmask_b32_e32 v2, 0, v72, vcc
	v_fmac_f32_e32 v2, 2.0, v73
	v_cmp_gt_f32_e32 vcc, s45, v0
	v_exp_f32_e32 v2, v2
	s_cselect_b32 s8, 0xffffffc0, 0
	v_cndmask_b32_e32 v0, 0, v72, vcc
	v_fmac_f32_e32 v0, 4.0, v73
	v_exp_f32_e32 v0, v0
	v_mul_f32_e32 v1, 0x40400000, v73
	v_ldexp_f32 v74, v2, s8
	s_and_b64 s[8:9], vcc, exec
	s_cselect_b32 s8, 0xffffffc0, 0
	v_cmp_gt_f32_e32 vcc, s45, v1
	v_ldexp_f32 v75, v0, s8
	s_and_b64 s[8:9], vcc, exec
	v_cndmask_b32_e32 v0, 0, v72, vcc
	v_fmac_f32_e32 v0, 0x40400000, v73
	v_cmp_gt_f32_e32 vcc, s45, v73
	v_exp_f32_e32 v0, v0
	s_cselect_b32 s8, 0xffffffc0, 0
	v_cndmask_b32_e32 v1, 0, v72, vcc
	v_add_f32_e32 v1, v73, v1
	v_exp_f32_e32 v1, v1
	v_ldexp_f32 v76, v0, s8
	s_and_b64 s[8:9], vcc, exec
	s_cselect_b32 s8, 0xffffffc0, 0
	v_ldexp_f32 v77, v1, s8
	s_lshl_b32 s8, s44, 8
	s_add_u32 s30, s4, s8
	s_addc_u32 s31, s5, 0
	s_add_u32 s34, s18, s8
	s_addc_u32 s35, s19, 0
	s_lshr_b32 s8, s49, 4
	s_add_i32 s4, s8, 0x4200
	s_lshl_b32 s5, s8, 9
	s_lshl_b32 s9, s2, 5
	s_lshl_b32 s8, s8, 2
	s_add_i32 s55, s9, 0xfffff000
	s_add_i32 s56, s8, 0x4010
	v_mov_b32_e32 v25, 0
	s_movk_i32 s60, 0xff
	s_mov_b64 s[36:37], 0xe00
	s_movk_i32 s61, 0xff90
	s_movk_i32 s62, 0x1e00
	s_movk_i32 s63, 0x1000
	v_mov_b32_e32 v78, 0x3727c5ac
	s_movk_i32 s64, 0x7fff
	s_movk_i32 s65, 0x600
	v_mov_b32_e32 v79, 0x80000
	v_not_b32_e32 v80, 63
	v_mov_b32_e32 v81, 0xffffe000
	s_waitcnt vmcnt(0)
	s_nop 0
	s_branch .LBB0_659
